# MoBA QK: K fragments fetched two key groups ahead, score tiles accumulated in their final registers
# baseline (speedup 1.0000x reference)
.LBB0_151:
	s_ashr_i32 s0, s51, 1
	s_sub_i32 s0, s47, s0
	s_lshl_b32 s0, 1, s0
	s_and_b32 s1, s0, s49
	s_cmp_eq_u32 s1, 0
	s_cbranch_scc1 .LBB0_137
	s_mul_i32 s1, s15, 0x11000
	s_add_i32 s1, s1, 0
	v_add_u32_e32 v84, s1, v167
	v_add_u32_e32 v195, v84, v158
	v_add3_u32 v197, s1, v158, v167
	ds_read_b128 v[108:111], v195
	ds_read_b128 v[104:107], v195 offset:64
	ds_read_b128 v[100:103], v195 offset:128
	ds_read_b128 v[96:99], v195 offset:192
	ds_read_b128 v[92:95], v195 offset:272
	ds_read_b128 v[88:91], v195 offset:336
	ds_read_b128 v[84:87], v195 offset:400
	ds_read_b128 v[198:201], v195 offset:464
	ds_read_b128 v[202:205], v195 offset:8704
	ds_read_b128 v[206:209], v195 offset:8768
	ds_read_b128 v[230:233], v195 offset:8832
	ds_read_b128 v[234:237], v195 offset:8896
	ds_read_b128 v[238:241], v195 offset:8976
	ds_read_b128 v[242:245], v195 offset:9040
	ds_read_b128 v[246:249], v195 offset:9104
	s_waitcnt lgkmcnt(11)
	v_mfma_f32_16x16x32_bf16 v[112:115], v[108:111], v[36:39], 0
	v_mfma_f32_16x16x32_bf16 v[112:115], v[104:107], v[40:43], v[112:115]
	v_mfma_f32_16x16x32_bf16 v[112:115], v[100:103], v[44:47], v[112:115]
	v_mfma_f32_16x16x32_bf16 v[112:115], v[96:99], v[48:51], v[112:115]
	ds_read_b128 v[96:99], v195 offset:9168
	s_waitcnt lgkmcnt(8)
	v_mfma_f32_16x16x32_bf16 v[108:111], v[92:95], v[36:39], 0
	v_mfma_f32_16x16x32_bf16 v[108:111], v[88:91], v[40:43], v[108:111]
	v_mfma_f32_16x16x32_bf16 v[108:111], v[84:87], v[44:47], v[108:111]
	v_mfma_f32_16x16x32_bf16 v[108:111], v[198:201], v[48:51], v[108:111]
	ds_read_b128 v[92:95], v195 offset:17408
	ds_read_b128 v[88:91], v195 offset:17472
	ds_read_b128 v[84:87], v195 offset:17536
	ds_read_b128 v[198:201], v195 offset:17600
	s_waitcnt lgkmcnt(8)
	v_mfma_f32_16x16x32_bf16 v[104:107], v[202:205], v[36:39], 0
	v_mfma_f32_16x16x32_bf16 v[104:107], v[206:209], v[40:43], v[104:107]
	v_mfma_f32_16x16x32_bf16 v[104:107], v[230:233], v[44:47], v[104:107]
	v_mfma_f32_16x16x32_bf16 v[104:107], v[234:237], v[48:51], v[104:107]
	ds_read_b128 v[202:205], v195 offset:17680
	ds_read_b128 v[206:209], v195 offset:17744
	ds_read_b128 v[230:233], v195 offset:17808
	ds_read_b128 v[234:237], v195 offset:17872
	s_waitcnt lgkmcnt(8)
	v_mfma_f32_16x16x32_bf16 v[100:103], v[238:241], v[36:39], 0
	v_mfma_f32_16x16x32_bf16 v[100:103], v[242:245], v[40:43], v[100:103]
	v_mfma_f32_16x16x32_bf16 v[100:103], v[246:249], v[44:47], v[100:103]
	v_mfma_f32_16x16x32_bf16 v[100:103], v[96:99], v[48:51], v[100:103]
	ds_read_b128 v[238:241], v195 offset:26112
	ds_read_b128 v[242:245], v195 offset:26176
	ds_read_b128 v[246:249], v195 offset:26240
	s_waitcnt lgkmcnt(7)
	v_mfma_f32_16x16x32_bf16 v[96:99], v[92:95], v[36:39], 0
	v_mfma_f32_16x16x32_bf16 v[96:99], v[88:91], v[40:43], v[96:99]
	v_mfma_f32_16x16x32_bf16 v[96:99], v[84:87], v[44:47], v[96:99]
	v_mfma_f32_16x16x32_bf16 v[96:99], v[198:201], v[48:51], v[96:99]
	ds_read_b128 v[198:201], v195 offset:26304
	s_waitcnt lgkmcnt(4)
	v_mfma_f32_16x16x32_bf16 v[92:95], v[202:205], v[36:39], 0
	v_mfma_f32_16x16x32_bf16 v[92:95], v[206:209], v[40:43], v[92:95]
	v_mfma_f32_16x16x32_bf16 v[92:95], v[230:233], v[44:47], v[92:95]
	v_mfma_f32_16x16x32_bf16 v[92:95], v[234:237], v[48:51], v[92:95]
	ds_read_b128 v[202:205], v195 offset:26384
	ds_read_b128 v[206:209], v195 offset:26448
	ds_read_b128 v[230:233], v195 offset:26512
	ds_read_b128 v[234:237], v195 offset:26576
	s_waitcnt lgkmcnt(4)
	v_mfma_f32_16x16x32_bf16 v[88:91], v[238:241], v[36:39], 0
	v_mfma_f32_16x16x32_bf16 v[88:91], v[242:245], v[40:43], v[88:91]
	v_mfma_f32_16x16x32_bf16 v[88:91], v[246:249], v[44:47], v[88:91]
	v_mfma_f32_16x16x32_bf16 v[88:91], v[198:201], v[48:51], v[88:91]
	s_waitcnt lgkmcnt(0)
	v_mfma_f32_16x16x32_bf16 v[84:87], v[202:205], v[36:39], 0
	v_mfma_f32_16x16x32_bf16 v[84:87], v[206:209], v[40:43], v[84:87]
	v_mfma_f32_16x16x32_bf16 v[84:87], v[230:233], v[44:47], v[84:87]
	v_mfma_f32_16x16x32_bf16 v[84:87], v[234:237], v[48:51], v[84:87]
	ds_read_b128 v[202:205], v195 offset:34816
	ds_read_b128 v[206:209], v195 offset:35088
	ds_read_b128 v[230:233], v195 offset:43520
	ds_read_b128 v[234:237], v195 offset:43792
	v_and_b32_e32 v197, s0, v139
	v_cmp_eq_u32_e64 s[0:1], 0, v197
	s_cmp_lt_u32 s51, 2
	s_mov_b64 s[10:11], -1
	s_cbranch_scc1 .LBB0_154
	v_max3_f32 v197, v112, v113, v114
	v_max3_f32 v198, v96, v97, v98
	v_max3_f32 v197, v197, v115, v108
	v_max3_f32 v198, v198, v99, v92
	v_max3_f32 v197, v197, v109, v110
	v_max3_f32 v198, v198, v93, v94
	v_max3_f32 v197, v197, v111, v104
	v_max3_f32 v198, v198, v95, v88
	v_max3_f32 v197, v197, v105, v106
	v_max3_f32 v198, v198, v89, v90
	v_max3_f32 v197, v197, v107, v100
	v_max3_f32 v198, v198, v91, v84
	v_max3_f32 v197, v197, v101, v102
	v_max3_f32 v198, v198, v85, v86
	v_max_f32_e32 v197, v197, v103
	v_max_f32_e32 v198, v198, v87
	v_max_f32_e32 v197, v197, v198
	v_cndmask_b32_e64 v197, v197, v215, s[0:1]
	s_mov_b64 s[10:11], 0
